# indexer scoring key transform: sign mask via ashr/or instead of cmp/cndmask
# speedup vs baseline: 1.2442x; 1.0019x over previous
.LBB0_621:
	s_add_i32 s30, s37, -9
	s_cmp_ge_i32 s30, s34
	s_cbranch_scc1 .LBB0_632
	s_waitcnt vmcnt(19)
	v_mfma_f32_16x16x32_bf16 v[228:231], v[0:3], v[92:95], 0
	v_mfma_f32_16x16x32_bf16 v[92:95], v[12:15], v[92:95], 0
	s_waitcnt vmcnt(18)
	v_mfma_f32_16x16x32_bf16 v[228:231], v[4:7], v[88:91], v[228:231]
	v_mfma_f32_16x16x32_bf16 v[88:91], v[16:19], v[88:91], v[92:95]
	s_nop 6
	v_max_f32_e32 v228, 0, v228
	v_max_f32_e32 v229, 0, v229
	v_max_f32_e32 v230, 0, v230
	v_max_f32_e32 v231, 0, v231
	v_pk_mul_f32 v[228:229], v[8:9], v[228:229]
	v_pk_mul_f32 v[230:231], v[10:11], v[230:231]
	v_add_f32_e32 v135, v228, v229
	v_add_f32_e32 v135, v230, v135
	v_max_f32_e32 v88, 0, v88
	v_max_f32_e32 v89, 0, v89
	v_add_f32_e32 v135, v231, v135
	v_pk_mul_f32 v[88:89], v[20:21], v[88:89]
	v_max_f32_e32 v90, 0, v90
	v_max_f32_e32 v91, 0, v91
	v_cvt_f16_f32_e32 v135, v135
	v_pk_mul_f32 v[90:91], v[22:23], v[90:91]
	v_add_f32_e32 v88, v88, v89
	v_add_f32_e32 v88, v90, v88
	v_add_f32_e32 v88, v91, v88
	v_cvt_f16_f32_e32 v88, v88
	v_cmp_ne_u16_e32 vcc, s33, v135
	s_nop 1
	v_cndmask_b32_e32 v135, 0, v135, vcc
	v_ashrrev_i16_e32 v89, 15, v135
	v_or_b32_e32 v89, s33, v89
	v_cmp_ne_u16_e32 vcc, s33, v88
	v_xor_b32_e32 v89, v89, v135
	ds_write_b16 v122, v89
	v_cndmask_b32_e32 v88, 0, v88, vcc
	v_ashrrev_i16_e32 v89, 15, v88
	v_or_b32_e32 v89, s33, v89
	v_xor_b32_e32 v88, v89, v88
	ds_write_b16 v122, v88 offset:32768
	s_add_i32 s30, s37, -8
	s_cmp_ge_i32 s30, s34
	s_cbranch_scc0 .LBB0_633

.LBB0_624:
	s_waitcnt vmcnt(15)
	v_mfma_f32_16x16x32_bf16 v[72:75], v[0:3], v[60:63], 0
	v_mfma_f32_16x16x32_bf16 v[60:63], v[12:15], v[60:63], 0
	s_waitcnt vmcnt(14)
	v_mfma_f32_16x16x32_bf16 v[72:75], v[4:7], v[56:59], v[72:75]
	v_mfma_f32_16x16x32_bf16 v[56:59], v[16:19], v[56:59], v[60:63]
	s_nop 6
	v_max_f32_e32 v72, 0, v72
	v_max_f32_e32 v73, 0, v73
	v_max_f32_e32 v74, 0, v74
	v_max_f32_e32 v75, 0, v75
	v_pk_mul_f32 v[72:73], v[8:9], v[72:73]
	v_pk_mul_f32 v[74:75], v[10:11], v[74:75]
	v_add_f32_e32 v72, v72, v73
	v_add_f32_e32 v72, v74, v72
	v_max_f32_e32 v56, 0, v56
	v_max_f32_e32 v57, 0, v57
	v_add_f32_e32 v72, v75, v72
	v_pk_mul_f32 v[56:57], v[20:21], v[56:57]
	v_max_f32_e32 v58, 0, v58
	v_max_f32_e32 v59, 0, v59
	v_cvt_f16_f32_e32 v72, v72
	v_pk_mul_f32 v[58:59], v[22:23], v[58:59]
	v_add_f32_e32 v56, v56, v57
	v_add_f32_e32 v56, v58, v56
	v_add_f32_e32 v56, v59, v56
	v_cvt_f16_f32_e32 v56, v56
	v_cmp_ne_u16_e32 vcc, s33, v72
	s_nop 1
	v_cndmask_b32_e32 v72, 0, v72, vcc
	v_ashrrev_i16_e32 v57, 15, v72
	v_or_b32_e32 v57, s33, v57
	v_cmp_ne_u16_e32 vcc, s33, v56
	v_xor_b32_e32 v57, v57, v72
	ds_write_b16 v122, v57 offset:256
	v_cndmask_b32_e32 v56, 0, v56, vcc
	v_ashrrev_i16_e32 v57, 15, v56
	v_or_b32_e32 v57, s33, v57
	v_xor_b32_e32 v56, v57, v56
	ds_write_b16 v122, v56 offset:33024
	s_add_i32 s30, s37, -6
	s_cmp_ge_i32 s30, s34
	s_cbranch_scc0 .LBB0_635

.LBB0_626:
	s_waitcnt vmcnt(11)
	v_mfma_f32_16x16x32_bf16 v[40:43], v[0:3], v[28:31], 0
	v_mfma_f32_16x16x32_bf16 v[28:31], v[12:15], v[28:31], 0
	s_waitcnt vmcnt(10)
	v_mfma_f32_16x16x32_bf16 v[40:43], v[4:7], v[24:27], v[40:43]
	v_mfma_f32_16x16x32_bf16 v[24:27], v[16:19], v[24:27], v[28:31]
	s_nop 6
	v_max_f32_e32 v40, 0, v40
	v_max_f32_e32 v41, 0, v41
	v_max_f32_e32 v42, 0, v42
	v_max_f32_e32 v43, 0, v43
	v_pk_mul_f32 v[40:41], v[8:9], v[40:41]
	v_pk_mul_f32 v[42:43], v[10:11], v[42:43]
	v_add_f32_e32 v40, v40, v41
	v_add_f32_e32 v40, v42, v40
	v_max_f32_e32 v24, 0, v24
	v_max_f32_e32 v25, 0, v25
	v_add_f32_e32 v40, v43, v40
	v_pk_mul_f32 v[24:25], v[20:21], v[24:25]
	v_max_f32_e32 v26, 0, v26
	v_max_f32_e32 v27, 0, v27
	v_cvt_f16_f32_e32 v40, v40
	v_pk_mul_f32 v[26:27], v[22:23], v[26:27]
	v_add_f32_e32 v24, v24, v25
	v_add_f32_e32 v24, v26, v24
	v_add_f32_e32 v24, v27, v24
	v_cvt_f16_f32_e32 v24, v24
	v_cmp_ne_u16_e32 vcc, s33, v40
	s_nop 1
	v_cndmask_b32_e32 v40, 0, v40, vcc
	v_ashrrev_i16_e32 v25, 15, v40
	v_or_b32_e32 v25, s33, v25
	v_cmp_ne_u16_e32 vcc, s33, v24
	v_xor_b32_e32 v25, v25, v40
	ds_write_b16 v122, v25 offset:512
	v_cndmask_b32_e32 v24, 0, v24, vcc
	v_ashrrev_i16_e32 v25, 15, v24
	v_or_b32_e32 v25, s33, v25
	v_xor_b32_e32 v24, v25, v24
	ds_write_b16 v122, v24 offset:33280
.LBB0_627:
	s_add_i32 s30, s37, 1
	s_min_i32 s30, s30, s35
	s_max_i32 s30, s30, 0
	s_lshl_b32 s30, s30, 2
	s_add_i32 s30, s30, s28
	s_lshl_b64 s[38:39], s[30:31], 11
	s_add_i32 s30, s37, 2
	s_min_i32 s30, s30, s35
	s_max_i32 s30, s30, 0
	s_lshl_b32 s30, s30, 2
	s_add_i32 s30, s30, s28
	s_waitcnt vmcnt(10)
	v_lshl_add_u64 v[24:25], v[140:141], 0, s[38:39]
	s_lshl_b64 s[38:39], s[30:31], 11
	s_add_i32 s30, s37, 3
	s_min_i32 s30, s30, s35
	s_max_i32 s30, s30, 0
	s_lshl_b32 s30, s30, 2
	s_add_i32 s30, s30, s28
	global_load_dwordx4 v[92:95], v[24:25], off
	global_load_dwordx4 v[88:91], v[24:25], off offset:1024
	v_lshl_add_u64 v[24:25], v[140:141], 0, s[38:39]
	s_lshl_b64 s[38:39], s[30:31], 11
	s_add_i32 s30, s37, 4
	s_min_i32 s30, s30, s35
	s_max_i32 s30, s30, 0
	s_lshl_b32 s30, s30, 2
	s_add_i32 s30, s30, s28
	global_load_dwordx4 v[76:79], v[24:25], off
	global_load_dwordx4 v[72:75], v[24:25], off offset:1024
	v_lshl_add_u64 v[24:25], v[140:141], 0, s[38:39]
	s_lshl_b64 s[38:39], s[30:31], 11
	s_add_i32 s30, s37, 5
	s_min_i32 s30, s30, s35
	s_max_i32 s30, s30, 0
	s_lshl_b32 s30, s30, 2
	s_add_i32 s30, s30, s28
	global_load_dwordx4 v[60:63], v[24:25], off
	global_load_dwordx4 v[56:59], v[24:25], off offset:1024
	v_lshl_add_u64 v[24:25], v[140:141], 0, s[38:39]
	s_lshl_b64 s[38:39], s[30:31], 11
	global_load_dwordx4 v[44:47], v[24:25], off
	global_load_dwordx4 v[40:43], v[24:25], off offset:1024
	v_lshl_add_u64 v[24:25], v[140:141], 0, s[38:39]
	global_load_dwordx4 v[28:31], v[24:25], off
	s_nop 0
	global_load_dwordx4 v[24:27], v[24:25], off offset:1024
	s_add_i32 s30, s37, -4
	s_cmp_ge_i32 s30, s34
	s_cbranch_scc1 .LBB0_636
	s_waitcnt vmcnt(19)
	v_mfma_f32_16x16x32_bf16 v[228:231], v[0:3], v[100:103], 0
	v_mfma_f32_16x16x32_bf16 v[100:103], v[12:15], v[100:103], 0
	s_waitcnt vmcnt(18)
	v_mfma_f32_16x16x32_bf16 v[228:231], v[4:7], v[96:99], v[228:231]
	v_mfma_f32_16x16x32_bf16 v[96:99], v[16:19], v[96:99], v[100:103]
	s_nop 6
	v_max_f32_e32 v228, 0, v228
	v_max_f32_e32 v229, 0, v229
	v_max_f32_e32 v230, 0, v230
	v_max_f32_e32 v231, 0, v231
	v_pk_mul_f32 v[228:229], v[8:9], v[228:229]
	v_pk_mul_f32 v[230:231], v[10:11], v[230:231]
	v_add_f32_e32 v135, v228, v229
	v_add_f32_e32 v135, v230, v135
	v_max_f32_e32 v96, 0, v96
	v_max_f32_e32 v97, 0, v97
	v_add_f32_e32 v135, v231, v135
	v_pk_mul_f32 v[96:97], v[20:21], v[96:97]
	v_max_f32_e32 v98, 0, v98
	v_max_f32_e32 v99, 0, v99
	v_cvt_f16_f32_e32 v135, v135
	v_pk_mul_f32 v[98:99], v[22:23], v[98:99]
	v_add_f32_e32 v96, v96, v97
	v_add_f32_e32 v96, v98, v96
	v_add_f32_e32 v96, v99, v96
	v_cvt_f16_f32_e32 v96, v96
	v_cmp_ne_u16_e32 vcc, s33, v135
	s_nop 1
	v_cndmask_b32_e32 v135, 0, v135, vcc
	v_ashrrev_i16_e32 v97, 15, v135
	v_or_b32_e32 v97, s33, v97
	v_cmp_ne_u16_e32 vcc, s33, v96
	v_xor_b32_e32 v97, v97, v135
	ds_write_b16 v122, v97 offset:640
	v_cndmask_b32_e32 v96, 0, v96, vcc
	v_ashrrev_i16_e32 v97, 15, v96
	v_or_b32_e32 v97, s33, v97
	v_xor_b32_e32 v96, v97, v96
	ds_write_b16 v122, v96 offset:33408
	s_add_i32 s30, s37, -3
	s_cmp_ge_i32 s30, s34
	s_cbranch_scc0 .LBB0_637

.LBB0_630:
	s_waitcnt vmcnt(15)
	v_mfma_f32_16x16x32_bf16 v[80:83], v[0:3], v[68:71], 0
	v_mfma_f32_16x16x32_bf16 v[68:71], v[12:15], v[68:71], 0
	s_waitcnt vmcnt(14)
	v_mfma_f32_16x16x32_bf16 v[80:83], v[4:7], v[64:67], v[80:83]
	v_mfma_f32_16x16x32_bf16 v[64:67], v[16:19], v[64:67], v[68:71]
	s_nop 6
	v_max_f32_e32 v80, 0, v80
	v_max_f32_e32 v81, 0, v81
	v_max_f32_e32 v82, 0, v82
	v_max_f32_e32 v83, 0, v83
	v_pk_mul_f32 v[80:81], v[8:9], v[80:81]
	v_pk_mul_f32 v[82:83], v[10:11], v[82:83]
	v_add_f32_e32 v80, v80, v81
	v_add_f32_e32 v80, v82, v80
	v_max_f32_e32 v64, 0, v64
	v_max_f32_e32 v65, 0, v65
	v_add_f32_e32 v80, v83, v80
	v_pk_mul_f32 v[64:65], v[20:21], v[64:65]
	v_max_f32_e32 v66, 0, v66
	v_max_f32_e32 v67, 0, v67
	v_cvt_f16_f32_e32 v80, v80
	v_pk_mul_f32 v[66:67], v[22:23], v[66:67]
	v_add_f32_e32 v64, v64, v65
	v_add_f32_e32 v64, v66, v64
	v_add_f32_e32 v64, v67, v64
	v_cvt_f16_f32_e32 v64, v64
	v_cmp_ne_u16_e32 vcc, s33, v80
	s_nop 1
	v_cndmask_b32_e32 v80, 0, v80, vcc
	v_ashrrev_i16_e32 v65, 15, v80
	v_or_b32_e32 v65, s33, v65
	v_cmp_ne_u16_e32 vcc, s33, v64
	v_xor_b32_e32 v65, v65, v80
	ds_write_b16 v122, v65 offset:896
	v_cndmask_b32_e32 v64, 0, v64, vcc
	v_ashrrev_i16_e32 v65, 15, v64
	v_or_b32_e32 v65, s33, v65
	v_xor_b32_e32 v64, v65, v64
	ds_write_b16 v122, v64 offset:33664
	s_add_i32 s30, s37, -1
	s_cmp_ge_i32 s30, s34
	s_cbranch_scc0 .LBB0_639

.LBB0_633:
	s_waitcnt vmcnt(17)
	v_mfma_f32_16x16x32_bf16 v[88:91], v[0:3], v[76:79], 0
	v_mfma_f32_16x16x32_bf16 v[76:79], v[12:15], v[76:79], 0
	s_waitcnt vmcnt(16)
	v_mfma_f32_16x16x32_bf16 v[88:91], v[4:7], v[72:75], v[88:91]
	v_mfma_f32_16x16x32_bf16 v[72:75], v[16:19], v[72:75], v[76:79]
	s_nop 6
	v_max_f32_e32 v88, 0, v88
	v_max_f32_e32 v89, 0, v89
	v_max_f32_e32 v90, 0, v90
	v_max_f32_e32 v91, 0, v91
	v_pk_mul_f32 v[88:89], v[8:9], v[88:89]
	v_pk_mul_f32 v[90:91], v[10:11], v[90:91]
	v_add_f32_e32 v88, v88, v89
	v_add_f32_e32 v88, v90, v88
	v_max_f32_e32 v72, 0, v72
	v_max_f32_e32 v73, 0, v73
	v_add_f32_e32 v88, v91, v88
	v_pk_mul_f32 v[72:73], v[20:21], v[72:73]
	v_max_f32_e32 v74, 0, v74
	v_max_f32_e32 v75, 0, v75
	v_cvt_f16_f32_e32 v88, v88
	v_pk_mul_f32 v[74:75], v[22:23], v[74:75]
	v_add_f32_e32 v72, v72, v73
	v_add_f32_e32 v72, v74, v72
	v_add_f32_e32 v72, v75, v72
	v_cvt_f16_f32_e32 v72, v72
	v_cmp_ne_u16_e32 vcc, s33, v88
	s_nop 1
	v_cndmask_b32_e32 v88, 0, v88, vcc
	v_ashrrev_i16_e32 v73, 15, v88
	v_or_b32_e32 v73, s33, v73
	v_cmp_ne_u16_e32 vcc, s33, v72
	v_xor_b32_e32 v73, v73, v88
	ds_write_b16 v122, v73 offset:128
	v_cndmask_b32_e32 v72, 0, v72, vcc
	v_ashrrev_i16_e32 v73, 15, v72
	v_or_b32_e32 v73, s33, v73
	v_xor_b32_e32 v72, v73, v72
	ds_write_b16 v122, v72 offset:32896
	s_add_i32 s30, s37, -7
	s_cmp_ge_i32 s30, s34
	s_cbranch_scc0 .LBB0_624

.LBB0_635:
	s_waitcnt vmcnt(13)
	v_mfma_f32_16x16x32_bf16 v[56:59], v[0:3], v[44:47], 0
	v_mfma_f32_16x16x32_bf16 v[44:47], v[12:15], v[44:47], 0
	s_waitcnt vmcnt(12)
	v_mfma_f32_16x16x32_bf16 v[56:59], v[4:7], v[40:43], v[56:59]
	v_mfma_f32_16x16x32_bf16 v[40:43], v[16:19], v[40:43], v[44:47]
	s_nop 6
	v_max_f32_e32 v56, 0, v56
	v_max_f32_e32 v57, 0, v57
	v_max_f32_e32 v58, 0, v58
	v_max_f32_e32 v59, 0, v59
	v_pk_mul_f32 v[56:57], v[8:9], v[56:57]
	v_pk_mul_f32 v[58:59], v[10:11], v[58:59]
	v_add_f32_e32 v56, v56, v57
	v_add_f32_e32 v56, v58, v56
	v_max_f32_e32 v40, 0, v40
	v_max_f32_e32 v41, 0, v41
	v_add_f32_e32 v56, v59, v56
	v_pk_mul_f32 v[40:41], v[20:21], v[40:41]
	v_max_f32_e32 v42, 0, v42
	v_max_f32_e32 v43, 0, v43
	v_cvt_f16_f32_e32 v56, v56
	v_pk_mul_f32 v[42:43], v[22:23], v[42:43]
	v_add_f32_e32 v40, v40, v41
	v_add_f32_e32 v40, v42, v40
	v_add_f32_e32 v40, v43, v40
	v_cvt_f16_f32_e32 v40, v40
	v_cmp_ne_u16_e32 vcc, s33, v56
	s_nop 1
	v_cndmask_b32_e32 v56, 0, v56, vcc
	v_ashrrev_i16_e32 v41, 15, v56
	v_or_b32_e32 v41, s33, v41
	v_cmp_ne_u16_e32 vcc, s33, v40
	v_xor_b32_e32 v41, v41, v56
	ds_write_b16 v122, v41 offset:384
	v_cndmask_b32_e32 v40, 0, v40, vcc
	v_ashrrev_i16_e32 v41, 15, v40
	v_or_b32_e32 v41, s33, v41
	v_xor_b32_e32 v40, v41, v40
	ds_write_b16 v122, v40 offset:33152
	s_add_i32 s30, s37, -5
	s_cmp_ge_i32 s30, s34
	s_cbranch_scc0 .LBB0_626
	s_branch .LBB0_627

.LBB0_637:
	s_waitcnt vmcnt(17)
	v_mfma_f32_16x16x32_bf16 v[96:99], v[0:3], v[84:87], 0
	v_mfma_f32_16x16x32_bf16 v[84:87], v[12:15], v[84:87], 0
	s_waitcnt vmcnt(16)
	v_mfma_f32_16x16x32_bf16 v[96:99], v[4:7], v[80:83], v[96:99]
	v_mfma_f32_16x16x32_bf16 v[80:83], v[16:19], v[80:83], v[84:87]
	s_nop 6
	v_max_f32_e32 v96, 0, v96
	v_max_f32_e32 v97, 0, v97
	v_max_f32_e32 v98, 0, v98
	v_max_f32_e32 v99, 0, v99
	v_pk_mul_f32 v[96:97], v[8:9], v[96:97]
	v_pk_mul_f32 v[98:99], v[10:11], v[98:99]
	v_add_f32_e32 v96, v96, v97
	v_add_f32_e32 v96, v98, v96
	v_max_f32_e32 v80, 0, v80
	v_max_f32_e32 v81, 0, v81
	v_add_f32_e32 v96, v99, v96
	v_pk_mul_f32 v[80:81], v[20:21], v[80:81]
	v_max_f32_e32 v82, 0, v82
	v_max_f32_e32 v83, 0, v83
	v_cvt_f16_f32_e32 v96, v96
	v_pk_mul_f32 v[82:83], v[22:23], v[82:83]
	v_add_f32_e32 v80, v80, v81
	v_add_f32_e32 v80, v82, v80
	v_add_f32_e32 v80, v83, v80
	v_cvt_f16_f32_e32 v80, v80
	v_cmp_ne_u16_e32 vcc, s33, v96
	s_nop 1
	v_cndmask_b32_e32 v96, 0, v96, vcc
	v_ashrrev_i16_e32 v81, 15, v96
	v_or_b32_e32 v81, s33, v81
	v_cmp_ne_u16_e32 vcc, s33, v80
	v_xor_b32_e32 v81, v81, v96
	ds_write_b16 v122, v81 offset:768
	v_cndmask_b32_e32 v80, 0, v80, vcc
	v_ashrrev_i16_e32 v81, 15, v80
	v_or_b32_e32 v81, s33, v81
	v_xor_b32_e32 v80, v81, v80
	ds_write_b16 v122, v80 offset:33536
	s_add_i32 s30, s37, -2
	s_cmp_ge_i32 s30, s34
	s_cbranch_scc0 .LBB0_630

.LBB0_639:
	s_waitcnt vmcnt(13)
	v_mfma_f32_16x16x32_bf16 v[64:67], v[0:3], v[52:55], 0
	v_mfma_f32_16x16x32_bf16 v[52:55], v[12:15], v[52:55], 0
	s_waitcnt vmcnt(12)
	v_mfma_f32_16x16x32_bf16 v[64:67], v[4:7], v[48:51], v[64:67]
	v_mfma_f32_16x16x32_bf16 v[48:51], v[16:19], v[48:51], v[52:55]
	s_nop 6
	v_max_f32_e32 v64, 0, v64
	v_max_f32_e32 v65, 0, v65
	v_max_f32_e32 v66, 0, v66
	v_max_f32_e32 v67, 0, v67
	v_pk_mul_f32 v[64:65], v[8:9], v[64:65]
	v_pk_mul_f32 v[66:67], v[10:11], v[66:67]
	v_add_f32_e32 v64, v64, v65
	v_add_f32_e32 v64, v66, v64
	v_max_f32_e32 v48, 0, v48
	v_max_f32_e32 v49, 0, v49
	v_add_f32_e32 v64, v67, v64
	v_pk_mul_f32 v[48:49], v[20:21], v[48:49]
	v_max_f32_e32 v50, 0, v50
	v_max_f32_e32 v51, 0, v51
	v_cvt_f16_f32_e32 v64, v64
	v_pk_mul_f32 v[50:51], v[22:23], v[50:51]
	v_add_f32_e32 v48, v48, v49
	v_add_f32_e32 v48, v50, v48
	v_add_f32_e32 v48, v51, v48
	v_cvt_f16_f32_e32 v48, v48
	v_cmp_ne_u16_e32 vcc, s33, v64
	s_nop 1
	v_cndmask_b32_e32 v64, 0, v64, vcc
	v_ashrrev_i16_e32 v49, 15, v64
	v_or_b32_e32 v49, s33, v49
	v_cmp_ne_u16_e32 vcc, s33, v48
	v_xor_b32_e32 v49, v49, v64
	ds_write_b16 v122, v49 offset:1024
	v_cndmask_b32_e32 v48, 0, v48, vcc
	v_ashrrev_i16_e32 v49, 15, v48
	v_or_b32_e32 v49, s33, v49
	v_xor_b32_e32 v48, v49, v48
	ds_write_b16 v122, v48 offset:33792
	s_cmp_ge_i32 s37, s34
	s_cbranch_scc1 .LBB0_620
.LBB0_640:
	s_waitcnt vmcnt(11)
	v_mfma_f32_16x16x32_bf16 v[48:51], v[0:3], v[36:39], 0
	v_mfma_f32_16x16x32_bf16 v[36:39], v[12:15], v[36:39], 0
	s_waitcnt vmcnt(10)
	v_mfma_f32_16x16x32_bf16 v[48:51], v[4:7], v[32:35], v[48:51]
	v_mfma_f32_16x16x32_bf16 v[32:35], v[16:19], v[32:35], v[36:39]
	s_nop 6
	v_max_f32_e32 v48, 0, v48
	v_max_f32_e32 v49, 0, v49
	v_max_f32_e32 v50, 0, v50
	v_max_f32_e32 v51, 0, v51
	v_pk_mul_f32 v[48:49], v[8:9], v[48:49]
	v_pk_mul_f32 v[50:51], v[10:11], v[50:51]
	v_add_f32_e32 v48, v48, v49
	v_add_f32_e32 v48, v50, v48
	v_max_f32_e32 v32, 0, v32
	v_max_f32_e32 v33, 0, v33
	v_add_f32_e32 v48, v51, v48
	v_pk_mul_f32 v[32:33], v[20:21], v[32:33]
	v_max_f32_e32 v34, 0, v34
	v_max_f32_e32 v35, 0, v35
	v_cvt_f16_f32_e32 v48, v48
	v_pk_mul_f32 v[34:35], v[22:23], v[34:35]
	v_add_f32_e32 v32, v32, v33
	v_add_f32_e32 v32, v34, v32
	v_add_f32_e32 v32, v35, v32
	v_cvt_f16_f32_e32 v32, v32
	v_cmp_ne_u16_e32 vcc, s33, v48
	s_nop 1
	v_cndmask_b32_e32 v48, 0, v48, vcc
	v_ashrrev_i16_e32 v33, 15, v48
	v_or_b32_e32 v33, s33, v33
	v_cmp_ne_u16_e32 vcc, s33, v32
	v_xor_b32_e32 v33, v33, v48
	ds_write_b16 v122, v33 offset:1152
	v_cndmask_b32_e32 v32, 0, v32, vcc
	v_ashrrev_i16_e32 v33, 15, v32
	v_or_b32_e32 v33, s33, v33
	v_xor_b32_e32 v32, v33, v32
	ds_write_b16 v122, v32 offset:33920
	s_branch .LBB0_620
